# grid barrier: the 3rd-from-last arriver of each XCD starts an early L2 write-back
# speedup vs baseline: 1.0047x; 1.0047x over previous
.LBB0_91:
	s_or_b64 exec, exec, s[8:9]
	v_cvt_f32_u32_e32 v4, v2
	s_waitcnt vmcnt(0)
	v_readfirstlane_b32 s3, v3
	v_sub_u32_e32 v3, 0, v2
	v_rcp_iflag_f32_e32 v4, v4
	v_add_u32_e32 v5, s3, v0
	v_mul_f32_e32 v4, 0x4f7ffffe, v4
	v_cvt_u32_f32_e32 v4, v4
	v_mul_lo_u32 v0, v3, v4
	v_mul_hi_u32 v0, v4, v0
	v_add_u32_e32 v0, v4, v0
	v_mul_hi_u32 v0, v5, v0
	v_mul_lo_u32 v3, v0, v2
	v_sub_u32_e32 v3, v5, v3
	v_add_u32_e32 v4, 1, v0
	v_cmp_ge_u32_e32 vcc, v3, v2
	s_nop 1
	v_cndmask_b32_e32 v0, v0, v4, vcc
	v_sub_u32_e32 v4, v3, v2
	v_cndmask_b32_e32 v3, v3, v4, vcc
	v_add_u32_e32 v4, 1, v0
	v_cmp_ge_u32_e32 vcc, v3, v2
	v_add_u32_e32 v3, 1, v5
	s_nop 0
	v_cndmask_b32_e32 v0, v0, v4, vcc
	v_mul_lo_u32 v4, v2, v0
	v_add_u32_e32 v2, v4, v2
	v_cmp_ne_u32_e32 vcc, v3, v2
	s_and_saveexec_b64 s[6:7], vcc
	s_xor_b64 s[6:7], exec, s[6:7]
	s_cbranch_execz .LBB0_105
	s_waitcnt lgkmcnt(0)
	v_add_u32_e32 v1, 3, v3
	v_cmp_eq_u32_e32 vcc, v1, v2
	s_cbranch_vccz .Lbar_nowb_0
	buffer_wbl2 sc1
.Lbar_nowb_0:
	s_add_u32 s22, s26, 0xf465600
	s_addc_u32 s23, s27, 0
	v_mov_b32_e32 v1, 0
	global_load_dword v1, v1, s[22:23] sc1
	s_waitcnt vmcnt(0)
	v_cmp_eq_u32_e32 vcc, v1, v0
	s_and_saveexec_b64 s[8:9], vcc
	s_cbranch_execz .LBB0_104
	s_add_u32 s20, s26, 0xf462300
	s_addc_u32 s21, s27, 0
	s_mov_b32 s3, 1
	s_mov_b64 s[24:25], 0
	v_mov_b32_e32 v1, 0
	s_branch .LBB0_95

.Lbar_nowb_1:
	s_add_u32 s12, s26, 0xf465600
	s_addc_u32 s13, s27, 0
	v_mov_b32_e32 v1, 0
	global_load_dword v1, v1, s[12:13] sc1
	s_waitcnt vmcnt(0)
	v_cmp_eq_u32_e32 vcc, v1, v0
	s_and_saveexec_b64 s[8:9], vcc
	s_cbranch_execz .LBB0_316
	s_add_u32 s10, s26, 0xf462300
	s_addc_u32 s11, s27, 0
	s_mov_b32 s3, 1
	s_mov_b64 s[14:15], 0
	v_mov_b32_e32 v1, 0
	s_branch .LBB0_307

.LBB0_381:
	s_or_b64 exec, exec, s[8:9]
	v_cvt_f32_u32_e32 v5, v2
	s_waitcnt vmcnt(0)
	v_readfirstlane_b32 s6, v3
	v_sub_u32_e32 v3, 0, v2
	v_rcp_iflag_f32_e32 v5, v5
	v_add_u32_e32 v6, s6, v1
	v_mul_f32_e32 v5, 0x4f7ffffe, v5
	v_cvt_u32_f32_e32 v5, v5
	v_mul_lo_u32 v1, v3, v5
	v_mul_hi_u32 v1, v5, v1
	v_add_u32_e32 v1, v5, v1
	v_mul_hi_u32 v1, v6, v1
	v_mul_lo_u32 v3, v1, v2
	v_sub_u32_e32 v3, v6, v3
	v_add_u32_e32 v5, 1, v1
	v_cmp_ge_u32_e32 vcc, v3, v2
	s_nop 1
	v_cndmask_b32_e32 v1, v1, v5, vcc
	v_sub_u32_e32 v5, v3, v2
	v_cndmask_b32_e32 v3, v3, v5, vcc
	v_add_u32_e32 v5, 1, v1
	v_cmp_ge_u32_e32 vcc, v3, v2
	v_add_u32_e32 v3, 1, v6
	s_nop 0
	v_cndmask_b32_e32 v1, v1, v5, vcc
	v_mul_lo_u32 v5, v2, v1
	v_add_u32_e32 v2, v5, v2
	v_cmp_ne_u32_e32 vcc, v3, v2
	s_and_saveexec_b64 s[6:7], vcc
	s_xor_b64 s[6:7], exec, s[6:7]
	s_cbranch_execz .LBB0_395
	s_waitcnt lgkmcnt(0)
	v_add_u32_e32 v0, 3, v3
	v_cmp_eq_u32_e32 vcc, v0, v2
	s_cbranch_vccz .Lbar_nowb_2
	buffer_wbl2 sc1
.Lbar_nowb_2:
	s_add_u32 s10, s26, 0xf465600
	s_addc_u32 s11, s27, 0
	v_mov_b32_e32 v0, 0
	global_load_dword v0, v0, s[10:11] sc1
	s_waitcnt vmcnt(0)
	v_cmp_eq_u32_e32 vcc, v0, v1
	s_and_saveexec_b64 s[8:9], vcc
	s_cbranch_execz .LBB0_394
	s_mov_b32 s16, 1
	s_mov_b64 s[12:13], 0
	s_branch .LBB0_385

.Lbar_nowb_8:
	s_add_u32 s10, s26, 0xf465600
	s_addc_u32 s11, s27, 0
	v_mov_b32_e32 v0, 0
	global_load_dword v0, v0, s[10:11] sc1
	s_waitcnt vmcnt(0)
	v_cmp_eq_u32_e32 vcc, v0, v1
	s_and_saveexec_b64 s[8:9], vcc
	s_cbranch_execz .LBB0_1642
	s_mov_b32 s22, 1
	s_mov_b64 s[12:13], 0
	s_branch .LBB0_1633
